# dependency-aware MFMA schedule for all 40 K-loop blocks (acc-forwarding pairs + operand sharing)
# speedup vs baseline: 1.0172x; 1.0013x over previous
; #define PG8_STAGE(bufoff, gbase, voff) do { _Pragma("unroll") for (int _i = 0; _i < 2; ++_i) \
;         __builtin_amdgcn_global_load_lds((const unsigned*)((const char*)(gbase) + (voff)[_i]), (PG8_LAS unsigned*)(lds + (bufoff) + ldsw + _i * 8192), 16, 0, 0); } while (0)
; #define PG8_LDA(dst, b, h) do { _Pragma("unroll") for (int m = 0; m < 4; ++m) _Pragma("unroll") for (int k = 0; k < 2; ++k) dst[m][k] = *(const PG8_LAS bf16x8*)(lds + PG8_SA(b, h) + aoff + m * 2048 + k * 1024); } while (0)
; #define PG8_LDB(dst, b, h) do { _Pragma("unroll") for (int n = 0; n < 2; ++n) _Pragma("unroll") for (int k = 0; k < 2; ++k) dst[n][k] = *(const PG8_LAS bf16x8*)(lds + PG8_SB(b, h) + boff + n * 2048 + k * 1024); } while (0)
; #define PG8_MMA(ai, bj, At, Bt) do { __builtin_amdgcn_s_setprio(1); _Pragma("unroll") for (int m = 0; m < 4; ++m) _Pragma("unroll") for (int n = 0; n < 2; ++n) _Pragma("unroll") for (int k = 0; k < 2; ++k) \
;         acc[ai][bj][m][n] = __builtin_amdgcn_mfma_f32_16x16x32_bf16(Bt[n][k], At[m][k], acc[ai][bj][m][n], 0, 0, 0); __builtin_amdgcn_s_setprio(0); } while (0)
; #define PG8_WAIT_V(n) asm volatile("s_waitcnt vmcnt(" #n ")" ::: "memory")
; #define PG8_WAIT_L(n) asm volatile("s_waitcnt lgkmcnt(" #n ")" ::: "memory")
; template <class Epi, class Sched, bool ALIGN_EPI = true>
; __device__ __forceinline__ void gemm_phase(PG8_LAS unsigned char* lds, const Gemm g, const Sched& S, const Epi& E, const int tid) {
;     ...
;         for (int t = 0; t < nt; t += 2) {
;             const bool last = (t == nt - 2);
;             const char* a1 = cA + (size_t)(t + 1) * kstep;
;             const char* a2 = last ? nA : cA + (size_t)(t + 2) * kstep; const char* b2 = last ? nB : cB + (size_t)(t + 2) * kstep;
;             const char* a3 = a2 + kstep; const char* b3 = b2 + kstep;
;             if (last && has_next) S.a_ready(nxt);
;             PG8_LDB(B0, 0, 0); PG8_LDB(B1, 0, 1); PG8_SCHED; PG8_LDA(At, 0, 0); PG8_STAGE(PG8_SA(1, 1), a1 + hstepA, voffA);
;             PG8_WAIT_V(8); PG8_WAIT_L(0); PG8_BAR; PG8_MMA(0, 0, At, B0); PG8_MMA(0, 1, At, B1); PG8_BAR; PG8_SCHED;
;             PG8_LDA(At, 0, 1); PG8_STAGE(PG8_SB(0, 0), b2, voffB); PG8_STAGE(PG8_SB(0, 1), b2 + hstepB, voffB); PG8_STAGE(PG8_SA(0, 0), a2, voffA);
;             PG8_WAIT_V(8); PG8_WAIT_L(0); PG8_BAR; PG8_MMA(1, 0, At, B0); PG8_MMA(1, 1, At, B1); PG8_BAR; PG8_SCHED;
.LBB0_426:
	s_add_u32 s15, s12, 0xfff80080
	s_addc_u32 s16, s13, -1
	s_add_i32 s17, 0, 0x10000
	s_cmp_eq_u32 s53, 4
	s_cselect_b32 s63, s1, s16
	s_cselect_b32 s62, s5, s15
	s_cselect_b32 s23, s8, s21
	s_cselect_b32 s22, s9, s20
	s_add_i32 s15, 0, 0x14000
	v_add_u32_e32 v72, s17, v251
	v_add_u32_e32 v136, s15, v251
	ds_read_b128 v[60:63], v72
	ds_read_b128 v[64:67], v72 offset:1024
	ds_read_b128 v[68:71], v72 offset:2048
	ds_read_b128 v[72:75], v72 offset:3072
	ds_read_b128 v[100:103], v136
	ds_read_b128 v[112:115], v136 offset:1024
	ds_read_b128 v[116:119], v136 offset:2048
	ds_read_b128 v[136:139], v136 offset:3072
	s_add_i32 m0, s11, 0xc000
	ds_read_b128 v[140:143], v252
	ds_read_b128 v[152:155], v252 offset:1024
	ds_read_b128 v[156:159], v252 offset:2048
	ds_read_b128 v[168:171], v252 offset:3072
	ds_read_b128 v[172:175], v252 offset:4096
	ds_read_b128 v[184:187], v252 offset:5120
	ds_read_b128 v[188:191], v252 offset:6144
	ds_read_b128 v[192:195], v252 offset:7168
	global_load_lds_dwordx4 v216, s[12:13]
	s_add_i32 m0, s11, 0xe000
	s_nop 0
	global_load_lds_dwordx4 v218, s[12:13]
	s_waitcnt vmcnt(8)
	s_waitcnt lgkmcnt(0)
	s_barrier
	s_waitcnt lgkmcnt(0)
	v_mfma_f32_16x16x32_bf16 v[180:183], v[60:63], v[140:143], v[180:183]
	v_mfma_f32_16x16x32_bf16 v[180:183], v[64:67], v[152:155], v[180:183]
	v_mfma_f32_16x16x32_bf16 v[176:179], v[72:75], v[152:155], v[176:179]
	v_mfma_f32_16x16x32_bf16 v[176:179], v[68:71], v[140:143], v[176:179]
	v_mfma_f32_16x16x32_bf16 v[144:147], v[68:71], v[156:159], v[144:147]
	v_mfma_f32_16x16x32_bf16 v[144:147], v[72:75], v[168:171], v[144:147]
	v_mfma_f32_16x16x32_bf16 v[148:151], v[64:67], v[168:171], v[148:151]
	v_mfma_f32_16x16x32_bf16 v[148:151], v[60:63], v[156:159], v[148:151]
	v_mfma_f32_16x16x32_bf16 v[124:127], v[60:63], v[172:175], v[124:127]
	v_mfma_f32_16x16x32_bf16 v[124:127], v[64:67], v[184:187], v[124:127]
	v_mfma_f32_16x16x32_bf16 v[120:123], v[72:75], v[184:187], v[120:123]
	v_mfma_f32_16x16x32_bf16 v[120:123], v[68:71], v[172:175], v[120:123]
	v_mfma_f32_16x16x32_bf16 v[92:95], v[68:71], v[188:191], v[92:95]
	v_mfma_f32_16x16x32_bf16 v[92:95], v[72:75], v[192:195], v[92:95]
	v_mfma_f32_16x16x32_bf16 v[96:99], v[64:67], v[192:195], v[96:99]
	v_mfma_f32_16x16x32_bf16 v[96:99], v[60:63], v[188:191], v[96:99]
	v_mfma_f32_16x16x32_bf16 v[164:167], v[100:103], v[140:143], v[164:167]
	v_mfma_f32_16x16x32_bf16 v[164:167], v[112:115], v[152:155], v[164:167]
	v_mfma_f32_16x16x32_bf16 v[132:135], v[112:115], v[168:171], v[132:135]
	v_mfma_f32_16x16x32_bf16 v[132:135], v[100:103], v[156:159], v[132:135]
	v_mfma_f32_16x16x32_bf16 v[128:131], v[116:119], v[156:159], v[128:131]
	v_mfma_f32_16x16x32_bf16 v[128:131], v[136:139], v[168:171], v[128:131]
	v_mfma_f32_16x16x32_bf16 v[104:107], v[136:139], v[184:187], v[104:107]
	v_mfma_f32_16x16x32_bf16 v[104:107], v[116:119], v[172:175], v[104:107]
	v_mfma_f32_16x16x32_bf16 v[108:111], v[100:103], v[172:175], v[108:111]
	v_mfma_f32_16x16x32_bf16 v[108:111], v[112:115], v[184:187], v[108:111]
	v_mfma_f32_16x16x32_bf16 v[88:91], v[112:115], v[192:195], v[88:91]
	v_mfma_f32_16x16x32_bf16 v[88:91], v[100:103], v[188:191], v[88:91]
	v_mfma_f32_16x16x32_bf16 v[84:87], v[116:119], v[188:191], v[84:87]
	v_mfma_f32_16x16x32_bf16 v[84:87], v[136:139], v[192:195], v[84:87]
	v_mfma_f32_16x16x32_bf16 v[140:143], v[116:119], v[140:143], v[160:163]
	v_mfma_f32_16x16x32_bf16 v[140:143], v[136:139], v[152:155], v[140:143]
	s_barrier
	s_add_i32 s16, s17, s67
	s_mov_b32 m0, s16
	ds_read_b128 v[152:155], v252 offset:16384
	ds_read_b128 v[156:159], v252 offset:17408
	ds_read_b128 v[160:163], v252 offset:18432
	ds_read_b128 v[168:171], v252 offset:19456
	ds_read_b128 v[172:175], v252 offset:20480
	ds_read_b128 v[184:187], v252 offset:21504
	ds_read_b128 v[188:191], v252 offset:22528
	ds_read_b128 v[192:195], v252 offset:23552
	global_load_lds_dwordx4 v2, s[22:23]
	s_add_i32 m0, s16, 0x2000
	s_add_u32 s78, s22, 0x20000
	s_addc_u32 s79, s23, 0
	s_add_i32 s15, s15, s67
	global_load_lds_dwordx4 v210, s[22:23]
	s_mov_b32 m0, s15
	s_nop 0
	global_load_lds_dwordx4 v2, s[78:79]
	s_add_i32 m0, s15, 0x2000
	s_nop 0
	global_load_lds_dwordx4 v210, s[78:79]
	s_mov_b32 m0, s11
	s_nop 0
	global_load_lds_dwordx4 v214, s[62:63]
	s_mov_b32 m0, s68
	s_nop 0
	global_load_lds_dwordx4 v212, s[62:63]
	s_waitcnt vmcnt(8)
	s_waitcnt lgkmcnt(0)
	s_barrier
	s_waitcnt lgkmcnt(0)
	v_mfma_f32_16x16x32_bf16 v[80:83], v[60:63], v[152:155], v[80:83]
	v_mfma_f32_16x16x32_bf16 v[80:83], v[64:67], v[156:159], v[80:83]
	v_mfma_f32_16x16x32_bf16 v[76:79], v[72:75], v[156:159], v[76:79]
	v_mfma_f32_16x16x32_bf16 v[76:79], v[68:71], v[152:155], v[76:79]
	v_mfma_f32_16x16x32_bf16 v[44:47], v[68:71], v[160:163], v[44:47]
	v_mfma_f32_16x16x32_bf16 v[44:47], v[72:75], v[168:171], v[44:47]
	v_mfma_f32_16x16x32_bf16 v[48:51], v[64:67], v[168:171], v[48:51]
	v_mfma_f32_16x16x32_bf16 v[48:51], v[60:63], v[160:163], v[48:51]
	v_mfma_f32_16x16x32_bf16 v[32:35], v[60:63], v[172:175], v[32:35]
	v_mfma_f32_16x16x32_bf16 v[32:35], v[64:67], v[184:187], v[32:35]
	v_mfma_f32_16x16x32_bf16 v[28:31], v[72:75], v[184:187], v[28:31]
	v_mfma_f32_16x16x32_bf16 v[28:31], v[68:71], v[172:175], v[28:31]
	v_mfma_f32_16x16x32_bf16 v[12:15], v[68:71], v[188:191], v[12:15]
	v_mfma_f32_16x16x32_bf16 v[12:15], v[72:75], v[192:195], v[12:15]
	v_mfma_f32_16x16x32_bf16 v[16:19], v[64:67], v[192:195], v[16:19]
	v_mfma_f32_16x16x32_bf16 v[16:19], v[60:63], v[188:191], v[16:19]
	v_mfma_f32_16x16x32_bf16 v[56:59], v[100:103], v[152:155], v[56:59]
	v_mfma_f32_16x16x32_bf16 v[56:59], v[112:115], v[156:159], v[56:59]
	v_mfma_f32_16x16x32_bf16 v[52:55], v[136:139], v[156:159], v[52:55]
	v_mfma_f32_16x16x32_bf16 v[52:55], v[116:119], v[152:155], v[52:55]
	v_mfma_f32_16x16x32_bf16 v[36:39], v[116:119], v[160:163], v[36:39]
	v_mfma_f32_16x16x32_bf16 v[36:39], v[136:139], v[168:171], v[36:39]
	v_mfma_f32_16x16x32_bf16 v[40:43], v[112:115], v[168:171], v[40:43]
	v_mfma_f32_16x16x32_bf16 v[40:43], v[100:103], v[160:163], v[40:43]
	v_mfma_f32_16x16x32_bf16 v[24:27], v[100:103], v[172:175], v[24:27]
	v_mfma_f32_16x16x32_bf16 v[24:27], v[112:115], v[184:187], v[24:27]
	v_mfma_f32_16x16x32_bf16 v[20:23], v[136:139], v[184:187], v[20:23]
	v_mfma_f32_16x16x32_bf16 v[20:23], v[116:119], v[172:175], v[20:23]
	v_mfma_f32_16x16x32_bf16 v[4:7], v[116:119], v[188:191], v[4:7]
	v_mfma_f32_16x16x32_bf16 v[4:7], v[136:139], v[192:195], v[4:7]
	v_mfma_f32_16x16x32_bf16 v[8:11], v[112:115], v[192:195], v[8:11]
	v_mfma_f32_16x16x32_bf16 v[8:11], v[100:103], v[188:191], v[8:11]
	s_barrier
; #define PG8_STAGE(bufoff, gbase, voff) do { _Pragma("unroll") for (int _i = 0; _i < 2; ++_i) \
;         __builtin_amdgcn_global_load_lds((const unsigned*)((const char*)(gbase) + (voff)[_i]), (PG8_LAS unsigned*)(lds + (bufoff) + ldsw + _i * 8192), 16, 0, 0); } while (0)
; #define PG8_LDA(dst, b, h) do { _Pragma("unroll") for (int m = 0; m < 4; ++m) _Pragma("unroll") for (int k = 0; k < 2; ++k) dst[m][k] = *(const PG8_LAS bf16x8*)(lds + PG8_SA(b, h) + aoff + m * 2048 + k * 1024); } while (0)
; #define PG8_LDB(dst, b, h) do { _Pragma("unroll") for (int n = 0; n < 2; ++n) _Pragma("unroll") for (int k = 0; k < 2; ++k) dst[n][k] = *(const PG8_LAS bf16x8*)(lds + PG8_SB(b, h) + boff + n * 2048 + k * 1024); } while (0)
; #define PG8_MMA(ai, bj, At, Bt) do { __builtin_amdgcn_s_setprio(1); _Pragma("unroll") for (int m = 0; m < 4; ++m) _Pragma("unroll") for (int n = 0; n < 2; ++n) _Pragma("unroll") for (int k = 0; k < 2; ++k) \
;         acc[ai][bj][m][n] = __builtin_amdgcn_mfma_f32_16x16x32_bf16(Bt[n][k], At[m][k], acc[ai][bj][m][n], 0, 0, 0); __builtin_amdgcn_s_setprio(0); } while (0)
; #define PG8_WAIT_V(n) asm volatile("s_waitcnt vmcnt(" #n ")" ::: "memory")
; #define PG8_WAIT_L(n) asm volatile("s_waitcnt lgkmcnt(" #n ")" ::: "memory")
; #define PG8_BAR __builtin_amdgcn_s_barrier()
; #define PG8_SCHED __builtin_amdgcn_sched_barrier(0)
; template <class Epi, class Sched, bool ALIGN_EPI = true>
; __device__ __forceinline__ void gemm_phase(PG8_LAS unsigned char* lds, const Gemm g, const Sched& S, const Epi& E, const int tid) {
;     ...
;             PG8_LDB(B0, 1, 0); PG8_LDB(B1, 1, 1); PG8_SCHED; PG8_LDA(At, 1, 0); PG8_STAGE(PG8_SA(0, 1), a2 + hstepA, voffA);
;             PG8_WAIT_V(8); PG8_WAIT_L(0); PG8_BAR; PG8_MMA(0, 0, At, B0); PG8_MMA(0, 1, At, B1); PG8_BAR; PG8_SCHED;
;             PG8_LDA(At, 1, 1); PG8_STAGE(PG8_SB(1, 0), b3, voffB); PG8_STAGE(PG8_SB(1, 1), b3 + hstepB, voffB); PG8_STAGE(PG8_SA(1, 0), a3, voffA);
;             PG8_WAIT_V(8); PG8_WAIT_L(0); PG8_BAR; PG8_MMA(1, 0, At, B0); PG8_MMA(1, 1, At, B1); PG8_BAR; PG8_SCHED;
;         }
;         if constexpr (ALIGN_EPI) { if (wr == 0) PG8_BAR; }
;         E(acc, cur, wr, wc, fr, fq); S.done(cur);
;         if (!has_next) break;
	s_add_i32 s15, 0, 0x18000
	s_add_i32 s16, 0, 0x1c000
	v_add_u32_e32 v72, s15, v251
	v_add_u32_e32 v136, s16, v251
	ds_read_b128 v[60:63], v72
	ds_read_b128 v[64:67], v72 offset:1024
	ds_read_b128 v[68:71], v72 offset:2048
	ds_read_b128 v[72:75], v72 offset:3072
	ds_read_b128 v[100:103], v136
	ds_read_b128 v[112:115], v136 offset:1024
	ds_read_b128 v[116:119], v136 offset:2048
	ds_read_b128 v[136:139], v136 offset:3072
	s_add_u32 s62, s62, 0x80000
	s_addc_u32 s63, s63, 0
	s_mov_b32 m0, s69
	ds_read_b128 v[152:155], v252 offset:32768
	ds_read_b128 v[156:159], v252 offset:33792
	ds_read_b128 v[168:171], v252 offset:34816
	ds_read_b128 v[172:175], v252 offset:35840
	ds_read_b128 v[184:187], v252 offset:36864
	ds_read_b128 v[188:191], v252 offset:37888
	ds_read_b128 v[192:195], v252 offset:38912
	ds_read_b128 v[196:199], v252 offset:39936
	global_load_lds_dwordx4 v214, s[62:63]
	s_mov_b32 m0, s70
	s_nop 0
	global_load_lds_dwordx4 v212, s[62:63]
	s_waitcnt vmcnt(8)
	s_waitcnt lgkmcnt(0)
	s_barrier
	s_waitcnt lgkmcnt(0)
	v_mfma_f32_16x16x32_bf16 v[160:163], v[60:63], v[152:155], v[180:183]
	v_mfma_f32_16x16x32_bf16 v[180:183], v[64:67], v[156:159], v[160:163]
	v_mfma_f32_16x16x32_bf16 v[148:151], v[64:67], v[172:175], v[148:151]
	v_mfma_f32_16x16x32_bf16 v[148:151], v[60:63], v[168:171], v[148:151]
	v_mfma_f32_16x16x32_bf16 v[144:147], v[68:71], v[168:171], v[144:147]
	v_mfma_f32_16x16x32_bf16 v[144:147], v[72:75], v[172:175], v[144:147]
	v_mfma_f32_16x16x32_bf16 v[120:123], v[72:75], v[188:191], v[120:123]
	v_mfma_f32_16x16x32_bf16 v[120:123], v[68:71], v[184:187], v[120:123]
	v_mfma_f32_16x16x32_bf16 v[160:163], v[68:71], v[152:155], v[176:179]
	v_mfma_f32_16x16x32_bf16 v[176:179], v[72:75], v[156:159], v[160:163]
	v_mfma_f32_16x16x32_bf16 v[92:95], v[72:75], v[196:199], v[92:95]
	v_mfma_f32_16x16x32_bf16 v[92:95], v[68:71], v[192:195], v[92:95]
	v_mfma_f32_16x16x32_bf16 v[96:99], v[60:63], v[192:195], v[96:99]
	v_mfma_f32_16x16x32_bf16 v[96:99], v[64:67], v[196:199], v[96:99]
	v_mfma_f32_16x16x32_bf16 v[124:127], v[64:67], v[188:191], v[124:127]
	v_mfma_f32_16x16x32_bf16 v[124:127], v[60:63], v[184:187], v[124:127]
	v_mfma_f32_16x16x32_bf16 v[160:163], v[100:103], v[152:155], v[164:167]
	v_mfma_f32_16x16x32_bf16 v[164:167], v[112:115], v[156:159], v[160:163]
	v_mfma_f32_16x16x32_bf16 v[132:135], v[112:115], v[172:175], v[132:135]
	v_mfma_f32_16x16x32_bf16 v[132:135], v[100:103], v[168:171], v[132:135]
	v_mfma_f32_16x16x32_bf16 v[128:131], v[116:119], v[168:171], v[128:131]
	v_mfma_f32_16x16x32_bf16 v[128:131], v[136:139], v[172:175], v[128:131]
	v_mfma_f32_16x16x32_bf16 v[104:107], v[136:139], v[188:191], v[104:107]
	v_mfma_f32_16x16x32_bf16 v[104:107], v[116:119], v[184:187], v[104:107]
	v_mfma_f32_16x16x32_bf16 v[140:143], v[116:119], v[152:155], v[140:143]
	v_mfma_f32_16x16x32_bf16 v[160:163], v[136:139], v[156:159], v[140:143]
	v_mfma_f32_16x16x32_bf16 v[84:87], v[136:139], v[196:199], v[84:87]
	v_mfma_f32_16x16x32_bf16 v[84:87], v[116:119], v[192:195], v[84:87]
	v_mfma_f32_16x16x32_bf16 v[88:91], v[100:103], v[192:195], v[88:91]
	v_mfma_f32_16x16x32_bf16 v[88:91], v[112:115], v[196:199], v[88:91]
	v_mfma_f32_16x16x32_bf16 v[108:111], v[112:115], v[188:191], v[108:111]
	v_mfma_f32_16x16x32_bf16 v[108:111], v[100:103], v[184:187], v[108:111]
	s_barrier
	s_add_i32 s15, s15, s67
	s_mov_b32 m0, s15
	ds_read_b128 v[140:143], v252 offset:49152
	ds_read_b128 v[152:155], v252 offset:50176
	ds_read_b128 v[156:159], v252 offset:51200
	ds_read_b128 v[168:171], v252 offset:52224
	ds_read_b128 v[172:175], v252 offset:53248
	ds_read_b128 v[184:187], v252 offset:54272
	ds_read_b128 v[188:191], v252 offset:55296
	ds_read_b128 v[192:195], v252 offset:56320
	s_add_u32 s98, s22, 0x80
	s_addc_u32 s99, s23, 0
	global_load_lds_dwordx4 v2, s[98:99]
	s_add_i32 m0, s15, 0x2000
	s_add_u32 s22, s22, 0x20080
	s_addc_u32 s23, s23, 0
	s_add_i32 s15, s16, s67
	global_load_lds_dwordx4 v210, s[98:99]
	s_mov_b32 m0, s15
	s_nop 0
	global_load_lds_dwordx4 v2, s[22:23]
	s_add_i32 m0, s15, 0x2000
	s_nop 0
	global_load_lds_dwordx4 v210, s[22:23]
	s_mov_b32 m0, s75
	s_nop 0
	s_add_u32 s98, s62, 0xfff80080
	s_addc_u32 s99, s63, -1
	global_load_lds_dwordx4 v214, s[98:99]
	s_mov_b32 m0, s76
	s_nop 0
	global_load_lds_dwordx4 v212, s[98:99]
	s_waitcnt vmcnt(8)
	s_waitcnt lgkmcnt(0)
	s_barrier
	s_waitcnt lgkmcnt(0)
	v_mfma_f32_16x16x32_bf16 v[80:83], v[60:63], v[140:143], v[80:83]
	v_mfma_f32_16x16x32_bf16 v[80:83], v[64:67], v[152:155], v[80:83]
	v_mfma_f32_16x16x32_bf16 v[76:79], v[72:75], v[152:155], v[76:79]
	v_mfma_f32_16x16x32_bf16 v[76:79], v[68:71], v[140:143], v[76:79]
	v_mfma_f32_16x16x32_bf16 v[44:47], v[68:71], v[156:159], v[44:47]
	v_mfma_f32_16x16x32_bf16 v[44:47], v[72:75], v[168:171], v[44:47]
	v_mfma_f32_16x16x32_bf16 v[48:51], v[64:67], v[168:171], v[48:51]
	v_mfma_f32_16x16x32_bf16 v[48:51], v[60:63], v[156:159], v[48:51]
	v_mfma_f32_16x16x32_bf16 v[32:35], v[60:63], v[172:175], v[32:35]
	v_mfma_f32_16x16x32_bf16 v[32:35], v[64:67], v[184:187], v[32:35]
	v_mfma_f32_16x16x32_bf16 v[28:31], v[72:75], v[184:187], v[28:31]
	v_mfma_f32_16x16x32_bf16 v[28:31], v[68:71], v[172:175], v[28:31]
	v_mfma_f32_16x16x32_bf16 v[12:15], v[68:71], v[188:191], v[12:15]
	v_mfma_f32_16x16x32_bf16 v[12:15], v[72:75], v[192:195], v[12:15]
	v_mfma_f32_16x16x32_bf16 v[16:19], v[64:67], v[192:195], v[16:19]
	v_mfma_f32_16x16x32_bf16 v[16:19], v[60:63], v[188:191], v[16:19]
	v_mfma_f32_16x16x32_bf16 v[56:59], v[100:103], v[140:143], v[56:59]
	v_mfma_f32_16x16x32_bf16 v[56:59], v[112:115], v[152:155], v[56:59]
	v_mfma_f32_16x16x32_bf16 v[52:55], v[136:139], v[152:155], v[52:55]
	v_mfma_f32_16x16x32_bf16 v[52:55], v[116:119], v[140:143], v[52:55]
	v_mfma_f32_16x16x32_bf16 v[36:39], v[116:119], v[156:159], v[36:39]
	v_mfma_f32_16x16x32_bf16 v[36:39], v[136:139], v[168:171], v[36:39]
	v_mfma_f32_16x16x32_bf16 v[40:43], v[112:115], v[168:171], v[40:43]
	v_mfma_f32_16x16x32_bf16 v[40:43], v[100:103], v[156:159], v[40:43]
	v_mfma_f32_16x16x32_bf16 v[24:27], v[100:103], v[172:175], v[24:27]
	v_mfma_f32_16x16x32_bf16 v[24:27], v[112:115], v[184:187], v[24:27]
	v_mfma_f32_16x16x32_bf16 v[20:23], v[136:139], v[184:187], v[20:23]
	v_mfma_f32_16x16x32_bf16 v[20:23], v[116:119], v[172:175], v[20:23]
	v_mfma_f32_16x16x32_bf16 v[4:7], v[116:119], v[188:191], v[4:7]
	v_mfma_f32_16x16x32_bf16 v[4:7], v[136:139], v[192:195], v[4:7]
	v_mfma_f32_16x16x32_bf16 v[8:11], v[112:115], v[192:195], v[8:11]
	v_mfma_f32_16x16x32_bf16 v[8:11], v[100:103], v[188:191], v[8:11]
	s_barrier
	s_add_i32 s53, s53, 2
	s_add_u32 s12, s12, 0x100
	s_addc_u32 s13, s13, 0
	s_add_u32 s20, s20, 0x100
	s_addc_u32 s21, s21, 0
	s_cmp_gt_u32 s53, 5
	s_cbranch_scc0 .LBB0_426
	s_and_b64 vcc, exec, s[48:49]
	s_cbranch_vccz .LBB0_429
	s_barrier

; #define PG8_STAGE(bufoff, gbase, voff) do { _Pragma("unroll") for (int _i = 0; _i < 2; ++_i) \
;         __builtin_amdgcn_global_load_lds((const unsigned*)((const char*)(gbase) + (voff)[_i]), (PG8_LAS unsigned*)(lds + (bufoff) + ldsw + _i * 8192), 16, 0, 0); } while (0)
; #define PG8_LDA(dst, b, h) do { _Pragma("unroll") for (int m = 0; m < 4; ++m) _Pragma("unroll") for (int k = 0; k < 2; ++k) dst[m][k] = *(const PG8_LAS bf16x8*)(lds + PG8_SA(b, h) + aoff + m * 2048 + k * 1024); } while (0)
; #define PG8_LDB(dst, b, h) do { _Pragma("unroll") for (int n = 0; n < 2; ++n) _Pragma("unroll") for (int k = 0; k < 2; ++k) dst[n][k] = *(const PG8_LAS bf16x8*)(lds + PG8_SB(b, h) + boff + n * 2048 + k * 1024); } while (0)
; #define PG8_MMA(ai, bj, At, Bt) do { __builtin_amdgcn_s_setprio(1); _Pragma("unroll") for (int m = 0; m < 4; ++m) _Pragma("unroll") for (int n = 0; n < 2; ++n) _Pragma("unroll") for (int k = 0; k < 2; ++k) \
;         acc[ai][bj][m][n] = __builtin_amdgcn_mfma_f32_16x16x32_bf16(Bt[n][k], At[m][k], acc[ai][bj][m][n], 0, 0, 0); __builtin_amdgcn_s_setprio(0); } while (0)
; #define PG8_WAIT_V(n) asm volatile("s_waitcnt vmcnt(" #n ")" ::: "memory")
; #define PG8_WAIT_L(n) asm volatile("s_waitcnt lgkmcnt(" #n ")" ::: "memory")
; template <class Epi, class Sched, bool ALIGN_EPI = true>
; __device__ __forceinline__ void gemm_phase(PG8_LAS unsigned char* lds, const Gemm g, const Sched& S, const Epi& E, const int tid) {
;     ...
;         for (int t = 0; t < nt; t += 2) {
;             const bool last = (t == nt - 2);
;             const char* a1 = cA + (size_t)(t + 1) * kstep;
;             const char* a2 = last ? nA : cA + (size_t)(t + 2) * kstep; const char* b2 = last ? nB : cB + (size_t)(t + 2) * kstep;
;             const char* a3 = a2 + kstep; const char* b3 = b2 + kstep;
;             if (last && has_next) S.a_ready(nxt);
;             PG8_LDB(B0, 0, 0); PG8_LDB(B1, 0, 1); PG8_SCHED; PG8_LDA(At, 0, 0); PG8_STAGE(PG8_SA(1, 1), a1 + hstepA, voffA);
;             PG8_WAIT_V(8); PG8_WAIT_L(0); PG8_BAR; PG8_MMA(0, 0, At, B0); PG8_MMA(0, 1, At, B1); PG8_BAR; PG8_SCHED;
;             PG8_LDA(At, 0, 1); PG8_STAGE(PG8_SB(0, 0), b2, voffB); PG8_STAGE(PG8_SB(0, 1), b2 + hstepB, voffB); PG8_STAGE(PG8_SA(0, 0), a2, voffA);
;             PG8_WAIT_V(8); PG8_WAIT_L(0); PG8_BAR; PG8_MMA(1, 0, At, B0); PG8_MMA(1, 1, At, B1); PG8_BAR; PG8_SCHED;
.LBB0_1087:
	s_add_i32 s45, s22, 2
	s_add_u32 s15, s12, 0xfff80080
	s_addc_u32 s16, s13, -1
	s_add_i32 s17, 0, 0x10000
	s_cmp_eq_u32 s1, s22
	s_cselect_b32 s55, s51, s16
	s_cselect_b32 s54, s50, s15
	s_cselect_b32 s23, s53, s21
	s_cselect_b32 s22, s52, s20
	s_add_i32 s15, 0, 0x14000
	v_add_u32_e32 v72, s17, v251
	v_add_u32_e32 v128, s15, v251
	ds_read_b128 v[56:59], v72
	ds_read_b128 v[64:67], v72 offset:1024
	ds_read_b128 v[68:71], v72 offset:2048
	ds_read_b128 v[72:75], v72 offset:3072
	ds_read_b128 v[92:95], v128
	ds_read_b128 v[104:107], v128 offset:1024
	ds_read_b128 v[116:119], v128 offset:2048
	ds_read_b128 v[128:131], v128 offset:3072
	s_add_i32 m0, s11, 0xc000
	ds_read_b128 v[140:143], v252
	ds_read_b128 v[152:155], v252 offset:1024
	ds_read_b128 v[156:159], v252 offset:2048
	ds_read_b128 v[160:163], v252 offset:3072
	ds_read_b128 v[172:175], v252 offset:4096
	ds_read_b128 v[184:187], v252 offset:5120
	ds_read_b128 v[188:191], v252 offset:6144
	ds_read_b128 v[192:195], v252 offset:7168
	global_load_lds_dwordx4 v216, s[12:13]
	s_add_i32 m0, s11, 0xe000
	s_nop 0
	global_load_lds_dwordx4 v218, s[12:13]
	s_waitcnt vmcnt(8)
	s_waitcnt lgkmcnt(0)
	s_barrier
	s_waitcnt lgkmcnt(0)
	v_mfma_f32_16x16x32_bf16 v[180:183], v[56:59], v[140:143], v[180:183]
	v_mfma_f32_16x16x32_bf16 v[180:183], v[64:67], v[152:155], v[180:183]
	v_mfma_f32_16x16x32_bf16 v[176:179], v[72:75], v[152:155], v[176:179]
	v_mfma_f32_16x16x32_bf16 v[176:179], v[68:71], v[140:143], v[176:179]
	v_mfma_f32_16x16x32_bf16 v[144:147], v[68:71], v[156:159], v[144:147]
	v_mfma_f32_16x16x32_bf16 v[144:147], v[72:75], v[160:163], v[144:147]
	v_mfma_f32_16x16x32_bf16 v[148:151], v[64:67], v[160:163], v[148:151]
	v_mfma_f32_16x16x32_bf16 v[148:151], v[56:59], v[156:159], v[148:151]
	v_mfma_f32_16x16x32_bf16 v[124:127], v[56:59], v[172:175], v[124:127]
	v_mfma_f32_16x16x32_bf16 v[124:127], v[64:67], v[184:187], v[124:127]
	v_mfma_f32_16x16x32_bf16 v[120:123], v[72:75], v[184:187], v[120:123]
	v_mfma_f32_16x16x32_bf16 v[120:123], v[68:71], v[172:175], v[120:123]
	v_mfma_f32_16x16x32_bf16 v[96:99], v[68:71], v[188:191], v[96:99]
	v_mfma_f32_16x16x32_bf16 v[96:99], v[72:75], v[192:195], v[96:99]
	v_mfma_f32_16x16x32_bf16 v[100:103], v[64:67], v[192:195], v[100:103]
	v_mfma_f32_16x16x32_bf16 v[100:103], v[56:59], v[188:191], v[100:103]
	v_mfma_f32_16x16x32_bf16 v[168:171], v[92:95], v[140:143], v[168:171]
	v_mfma_f32_16x16x32_bf16 v[168:171], v[104:107], v[152:155], v[168:171]
	v_mfma_f32_16x16x32_bf16 v[136:139], v[104:107], v[160:163], v[136:139]
	v_mfma_f32_16x16x32_bf16 v[136:139], v[92:95], v[156:159], v[136:139]
	v_mfma_f32_16x16x32_bf16 v[132:135], v[116:119], v[156:159], v[132:135]
	v_mfma_f32_16x16x32_bf16 v[132:135], v[128:131], v[160:163], v[132:135]
	v_mfma_f32_16x16x32_bf16 v[108:111], v[128:131], v[184:187], v[108:111]
	v_mfma_f32_16x16x32_bf16 v[108:111], v[116:119], v[172:175], v[108:111]
	v_mfma_f32_16x16x32_bf16 v[112:115], v[92:95], v[172:175], v[112:115]
	v_mfma_f32_16x16x32_bf16 v[112:115], v[104:107], v[184:187], v[112:115]
	v_mfma_f32_16x16x32_bf16 v[88:91], v[104:107], v[192:195], v[88:91]
	v_mfma_f32_16x16x32_bf16 v[88:91], v[92:95], v[188:191], v[88:91]
	v_mfma_f32_16x16x32_bf16 v[84:87], v[116:119], v[188:191], v[84:87]
	v_mfma_f32_16x16x32_bf16 v[84:87], v[128:131], v[192:195], v[84:87]
	v_mfma_f32_16x16x32_bf16 v[140:143], v[116:119], v[140:143], v[164:167]
	v_mfma_f32_16x16x32_bf16 v[140:143], v[128:131], v[152:155], v[140:143]
	s_barrier
	s_add_i32 s16, s17, s60
	s_mov_b32 m0, s16
	ds_read_b128 v[152:155], v252 offset:16384
	ds_read_b128 v[156:159], v252 offset:17408
	ds_read_b128 v[160:163], v252 offset:18432
	ds_read_b128 v[164:167], v252 offset:19456
	ds_read_b128 v[172:175], v252 offset:20480
	ds_read_b128 v[184:187], v252 offset:21504
	ds_read_b128 v[188:191], v252 offset:22528
	ds_read_b128 v[192:195], v252 offset:23552
	global_load_lds_dwordx4 v2, s[22:23]
	s_add_i32 m0, s16, 0x2000
	s_add_u32 s72, s22, 0x80000
	s_addc_u32 s73, s23, 0
	s_add_i32 s15, s15, s60
	global_load_lds_dwordx4 v214, s[22:23]
	s_mov_b32 m0, s15
	s_nop 0
	global_load_lds_dwordx4 v2, s[72:73]
	s_add_i32 m0, s15, 0x2000
	s_nop 0
	global_load_lds_dwordx4 v214, s[72:73]
	s_mov_b32 m0, s11
	s_nop 0
	global_load_lds_dwordx4 v210, s[54:55]
	s_mov_b32 m0, s61
	s_nop 0
	global_load_lds_dwordx4 v212, s[54:55]
	s_waitcnt vmcnt(8)
	s_waitcnt lgkmcnt(0)
	s_barrier
	s_waitcnt lgkmcnt(0)
	v_mfma_f32_16x16x32_bf16 v[80:83], v[56:59], v[152:155], v[80:83]
	v_mfma_f32_16x16x32_bf16 v[80:83], v[64:67], v[156:159], v[80:83]
	v_mfma_f32_16x16x32_bf16 v[76:79], v[72:75], v[156:159], v[76:79]
	v_mfma_f32_16x16x32_bf16 v[76:79], v[68:71], v[152:155], v[76:79]
	v_mfma_f32_16x16x32_bf16 v[44:47], v[68:71], v[160:163], v[44:47]
	v_mfma_f32_16x16x32_bf16 v[44:47], v[72:75], v[164:167], v[44:47]
	v_mfma_f32_16x16x32_bf16 v[48:51], v[64:67], v[164:167], v[48:51]
	v_mfma_f32_16x16x32_bf16 v[48:51], v[56:59], v[160:163], v[48:51]
	v_mfma_f32_16x16x32_bf16 v[32:35], v[56:59], v[172:175], v[32:35]
	v_mfma_f32_16x16x32_bf16 v[32:35], v[64:67], v[184:187], v[32:35]
	v_mfma_f32_16x16x32_bf16 v[28:31], v[72:75], v[184:187], v[28:31]
	v_mfma_f32_16x16x32_bf16 v[28:31], v[68:71], v[172:175], v[28:31]
	v_mfma_f32_16x16x32_bf16 v[12:15], v[68:71], v[188:191], v[12:15]
	v_mfma_f32_16x16x32_bf16 v[12:15], v[72:75], v[192:195], v[12:15]
	v_mfma_f32_16x16x32_bf16 v[16:19], v[64:67], v[192:195], v[16:19]
	v_mfma_f32_16x16x32_bf16 v[16:19], v[56:59], v[188:191], v[16:19]
	v_mfma_f32_16x16x32_bf16 v[52:55], v[116:119], v[152:155], v[52:55]
	v_mfma_f32_16x16x32_bf16 v[52:55], v[128:131], v[156:159], v[52:55]
	v_mfma_f32_16x16x32_bf16 v[36:39], v[128:131], v[164:167], v[36:39]
	v_mfma_f32_16x16x32_bf16 v[36:39], v[116:119], v[160:163], v[36:39]
	v_mfma_f32_16x16x32_bf16 v[40:43], v[92:95], v[160:163], v[40:43]
	v_mfma_f32_16x16x32_bf16 v[40:43], v[104:107], v[164:167], v[40:43]
	v_mfma_f32_16x16x32_bf16 v[24:27], v[104:107], v[184:187], v[24:27]
	v_mfma_f32_16x16x32_bf16 v[24:27], v[92:95], v[172:175], v[24:27]
	v_mfma_f32_16x16x32_bf16 v[20:23], v[116:119], v[172:175], v[20:23]
	v_mfma_f32_16x16x32_bf16 v[20:23], v[128:131], v[184:187], v[20:23]
	v_mfma_f32_16x16x32_bf16 v[4:7], v[128:131], v[192:195], v[4:7]
	v_mfma_f32_16x16x32_bf16 v[4:7], v[116:119], v[188:191], v[4:7]
	v_mfma_f32_16x16x32_bf16 v[8:11], v[92:95], v[188:191], v[8:11]
	v_mfma_f32_16x16x32_bf16 v[8:11], v[104:107], v[192:195], v[8:11]
	v_mfma_f32_16x16x32_bf16 v[56:59], v[92:95], v[152:155], v[60:63]
	v_mfma_f32_16x16x32_bf16 v[56:59], v[104:107], v[156:159], v[56:59]
	s_barrier
; #define PG8_STAGE(bufoff, gbase, voff) do { _Pragma("unroll") for (int _i = 0; _i < 2; ++_i) \
;         __builtin_amdgcn_global_load_lds((const unsigned*)((const char*)(gbase) + (voff)[_i]), (PG8_LAS unsigned*)(lds + (bufoff) + ldsw + _i * 8192), 16, 0, 0); } while (0)
; #define PG8_LDA(dst, b, h) do { _Pragma("unroll") for (int m = 0; m < 4; ++m) _Pragma("unroll") for (int k = 0; k < 2; ++k) dst[m][k] = *(const PG8_LAS bf16x8*)(lds + PG8_SA(b, h) + aoff + m * 2048 + k * 1024); } while (0)
; #define PG8_LDB(dst, b, h) do { _Pragma("unroll") for (int n = 0; n < 2; ++n) _Pragma("unroll") for (int k = 0; k < 2; ++k) dst[n][k] = *(const PG8_LAS bf16x8*)(lds + PG8_SB(b, h) + boff + n * 2048 + k * 1024); } while (0)
; #define PG8_MMA(ai, bj, At, Bt) do { __builtin_amdgcn_s_setprio(1); _Pragma("unroll") for (int m = 0; m < 4; ++m) _Pragma("unroll") for (int n = 0; n < 2; ++n) _Pragma("unroll") for (int k = 0; k < 2; ++k) \
;         acc[ai][bj][m][n] = __builtin_amdgcn_mfma_f32_16x16x32_bf16(Bt[n][k], At[m][k], acc[ai][bj][m][n], 0, 0, 0); __builtin_amdgcn_s_setprio(0); } while (0)
; #define PG8_WAIT_V(n) asm volatile("s_waitcnt vmcnt(" #n ")" ::: "memory")
; #define PG8_WAIT_L(n) asm volatile("s_waitcnt lgkmcnt(" #n ")" ::: "memory")
; #define PG8_BAR __builtin_amdgcn_s_barrier()
; #define PG8_SCHED __builtin_amdgcn_sched_barrier(0)
; template <class Epi, class Sched, bool ALIGN_EPI = true>
; __device__ __forceinline__ void gemm_phase(PG8_LAS unsigned char* lds, const Gemm g, const Sched& S, const Epi& E, const int tid) {
;     ...
;             PG8_LDB(B0, 1, 0); PG8_LDB(B1, 1, 1); PG8_SCHED; PG8_LDA(At, 1, 0); PG8_STAGE(PG8_SA(0, 1), a2 + hstepA, voffA);
;             PG8_WAIT_V(8); PG8_WAIT_L(0); PG8_BAR; PG8_MMA(0, 0, At, B0); PG8_MMA(0, 1, At, B1); PG8_BAR; PG8_SCHED;
;             PG8_LDA(At, 1, 1); PG8_STAGE(PG8_SB(1, 0), b3, voffB); PG8_STAGE(PG8_SB(1, 1), b3 + hstepB, voffB); PG8_STAGE(PG8_SA(1, 0), a3, voffA);
;             PG8_WAIT_V(8); PG8_WAIT_L(0); PG8_BAR; PG8_MMA(1, 0, At, B0); PG8_MMA(1, 1, At, B1); PG8_BAR; PG8_SCHED;
;         }
;         if constexpr (ALIGN_EPI) { if (wr == 0) PG8_BAR; }
;         E(acc, cur, wr, wc, fr, fq); S.done(cur);
;         if (!has_next) break;
	s_add_i32 s15, 0, 0x18000
	s_add_i32 s16, 0, 0x1c000
	v_add_u32_e32 v72, s15, v251
	v_add_u32_e32 v128, s16, v251
	ds_read_b128 v[60:63], v72
	ds_read_b128 v[64:67], v72 offset:1024
	ds_read_b128 v[68:71], v72 offset:2048
	ds_read_b128 v[72:75], v72 offset:3072
	ds_read_b128 v[92:95], v128
	ds_read_b128 v[104:107], v128 offset:1024
	ds_read_b128 v[116:119], v128 offset:2048
	ds_read_b128 v[128:131], v128 offset:3072
	s_add_u32 s54, s54, 0x80000
	s_addc_u32 s55, s55, 0
	s_mov_b32 m0, s62
	ds_read_b128 v[152:155], v252 offset:32768
	ds_read_b128 v[156:159], v252 offset:33792
	ds_read_b128 v[160:163], v252 offset:34816
	ds_read_b128 v[172:175], v252 offset:35840
	ds_read_b128 v[184:187], v252 offset:36864
	ds_read_b128 v[188:191], v252 offset:37888
	ds_read_b128 v[192:195], v252 offset:38912
	ds_read_b128 v[196:199], v252 offset:39936
	global_load_lds_dwordx4 v210, s[54:55]
	s_mov_b32 m0, s63
	s_nop 0
	global_load_lds_dwordx4 v212, s[54:55]
	s_waitcnt vmcnt(8)
	s_waitcnt lgkmcnt(0)
	s_barrier
	s_waitcnt lgkmcnt(0)
	v_mfma_f32_16x16x32_bf16 v[164:167], v[60:63], v[152:155], v[180:183]
	v_mfma_f32_16x16x32_bf16 v[180:183], v[64:67], v[156:159], v[164:167]
	v_mfma_f32_16x16x32_bf16 v[148:151], v[64:67], v[172:175], v[148:151]
	v_mfma_f32_16x16x32_bf16 v[148:151], v[60:63], v[160:163], v[148:151]
	v_mfma_f32_16x16x32_bf16 v[144:147], v[68:71], v[160:163], v[144:147]
	v_mfma_f32_16x16x32_bf16 v[144:147], v[72:75], v[172:175], v[144:147]
	v_mfma_f32_16x16x32_bf16 v[120:123], v[72:75], v[188:191], v[120:123]
	v_mfma_f32_16x16x32_bf16 v[120:123], v[68:71], v[184:187], v[120:123]
	v_mfma_f32_16x16x32_bf16 v[164:167], v[68:71], v[152:155], v[176:179]
	v_mfma_f32_16x16x32_bf16 v[176:179], v[72:75], v[156:159], v[164:167]
	v_mfma_f32_16x16x32_bf16 v[96:99], v[72:75], v[196:199], v[96:99]
	v_mfma_f32_16x16x32_bf16 v[96:99], v[68:71], v[192:195], v[96:99]
	v_mfma_f32_16x16x32_bf16 v[100:103], v[60:63], v[192:195], v[100:103]
	v_mfma_f32_16x16x32_bf16 v[100:103], v[64:67], v[196:199], v[100:103]
	v_mfma_f32_16x16x32_bf16 v[124:127], v[64:67], v[188:191], v[124:127]
	v_mfma_f32_16x16x32_bf16 v[124:127], v[60:63], v[184:187], v[124:127]
	v_mfma_f32_16x16x32_bf16 v[164:167], v[92:95], v[152:155], v[168:171]
	v_mfma_f32_16x16x32_bf16 v[168:171], v[104:107], v[156:159], v[164:167]
	v_mfma_f32_16x16x32_bf16 v[136:139], v[104:107], v[172:175], v[136:139]
	v_mfma_f32_16x16x32_bf16 v[136:139], v[92:95], v[160:163], v[136:139]
	v_mfma_f32_16x16x32_bf16 v[132:135], v[116:119], v[160:163], v[132:135]
	v_mfma_f32_16x16x32_bf16 v[132:135], v[128:131], v[172:175], v[132:135]
	v_mfma_f32_16x16x32_bf16 v[108:111], v[128:131], v[188:191], v[108:111]
	v_mfma_f32_16x16x32_bf16 v[108:111], v[116:119], v[184:187], v[108:111]
	v_mfma_f32_16x16x32_bf16 v[140:143], v[116:119], v[152:155], v[140:143]
	v_mfma_f32_16x16x32_bf16 v[164:167], v[128:131], v[156:159], v[140:143]
	v_mfma_f32_16x16x32_bf16 v[84:87], v[128:131], v[196:199], v[84:87]
	v_mfma_f32_16x16x32_bf16 v[84:87], v[116:119], v[192:195], v[84:87]
	v_mfma_f32_16x16x32_bf16 v[88:91], v[92:95], v[192:195], v[88:91]
	v_mfma_f32_16x16x32_bf16 v[88:91], v[104:107], v[196:199], v[88:91]
	v_mfma_f32_16x16x32_bf16 v[112:115], v[104:107], v[188:191], v[112:115]
	v_mfma_f32_16x16x32_bf16 v[112:115], v[92:95], v[184:187], v[112:115]
	s_barrier
	s_add_i32 s15, s15, s60
	s_mov_b32 m0, s15
	ds_read_b128 v[140:143], v252 offset:49152
	ds_read_b128 v[152:155], v252 offset:50176
	ds_read_b128 v[156:159], v252 offset:51200
	ds_read_b128 v[160:163], v252 offset:52224
	ds_read_b128 v[172:175], v252 offset:53248
	ds_read_b128 v[184:187], v252 offset:54272
	ds_read_b128 v[188:191], v252 offset:55296
	ds_read_b128 v[192:195], v252 offset:56320
	s_add_u32 s98, s22, 0x80
	s_addc_u32 s99, s23, 0
	global_load_lds_dwordx4 v2, s[98:99]
	s_add_i32 m0, s15, 0x2000
	s_add_u32 s22, s22, 0x80080
	s_addc_u32 s23, s23, 0
	s_add_i32 s15, s16, s60
	global_load_lds_dwordx4 v214, s[98:99]
	s_mov_b32 m0, s15
	s_nop 0
	global_load_lds_dwordx4 v2, s[22:23]
	s_add_i32 m0, s15, 0x2000
	s_nop 0
	global_load_lds_dwordx4 v214, s[22:23]
	s_mov_b32 m0, s68
	s_nop 0
	s_add_u32 s98, s54, 0xfff80080
	s_addc_u32 s99, s55, -1
	global_load_lds_dwordx4 v210, s[98:99]
	s_mov_b32 m0, s69
	s_nop 0
	global_load_lds_dwordx4 v212, s[98:99]
	s_waitcnt vmcnt(8)
	s_waitcnt lgkmcnt(0)
	s_barrier
	s_waitcnt lgkmcnt(0)
	v_mfma_f32_16x16x32_bf16 v[80:83], v[60:63], v[140:143], v[80:83]
	v_mfma_f32_16x16x32_bf16 v[80:83], v[64:67], v[152:155], v[80:83]
	v_mfma_f32_16x16x32_bf16 v[76:79], v[72:75], v[152:155], v[76:79]
	v_mfma_f32_16x16x32_bf16 v[76:79], v[68:71], v[140:143], v[76:79]
	v_mfma_f32_16x16x32_bf16 v[44:47], v[68:71], v[156:159], v[44:47]
	v_mfma_f32_16x16x32_bf16 v[44:47], v[72:75], v[160:163], v[44:47]
	v_mfma_f32_16x16x32_bf16 v[48:51], v[64:67], v[160:163], v[48:51]
	v_mfma_f32_16x16x32_bf16 v[48:51], v[60:63], v[156:159], v[48:51]
	v_mfma_f32_16x16x32_bf16 v[32:35], v[60:63], v[172:175], v[32:35]
	v_mfma_f32_16x16x32_bf16 v[32:35], v[64:67], v[184:187], v[32:35]
	v_mfma_f32_16x16x32_bf16 v[28:31], v[72:75], v[184:187], v[28:31]
	v_mfma_f32_16x16x32_bf16 v[28:31], v[68:71], v[172:175], v[28:31]
	v_mfma_f32_16x16x32_bf16 v[12:15], v[68:71], v[188:191], v[12:15]
	v_mfma_f32_16x16x32_bf16 v[12:15], v[72:75], v[192:195], v[12:15]
	v_mfma_f32_16x16x32_bf16 v[16:19], v[64:67], v[192:195], v[16:19]
	v_mfma_f32_16x16x32_bf16 v[16:19], v[60:63], v[188:191], v[16:19]
	v_mfma_f32_16x16x32_bf16 v[56:59], v[92:95], v[140:143], v[56:59]
	v_mfma_f32_16x16x32_bf16 v[60:63], v[104:107], v[152:155], v[56:59]
	v_mfma_f32_16x16x32_bf16 v[52:55], v[128:131], v[152:155], v[52:55]
	v_mfma_f32_16x16x32_bf16 v[52:55], v[116:119], v[140:143], v[52:55]
	v_mfma_f32_16x16x32_bf16 v[36:39], v[116:119], v[156:159], v[36:39]
	v_mfma_f32_16x16x32_bf16 v[36:39], v[128:131], v[160:163], v[36:39]
	v_mfma_f32_16x16x32_bf16 v[40:43], v[104:107], v[160:163], v[40:43]
	v_mfma_f32_16x16x32_bf16 v[40:43], v[92:95], v[156:159], v[40:43]
	v_mfma_f32_16x16x32_bf16 v[24:27], v[92:95], v[172:175], v[24:27]
	v_mfma_f32_16x16x32_bf16 v[24:27], v[104:107], v[184:187], v[24:27]
	v_mfma_f32_16x16x32_bf16 v[20:23], v[128:131], v[184:187], v[20:23]
	v_mfma_f32_16x16x32_bf16 v[20:23], v[116:119], v[172:175], v[20:23]
	v_mfma_f32_16x16x32_bf16 v[4:7], v[116:119], v[188:191], v[4:7]
	v_mfma_f32_16x16x32_bf16 v[4:7], v[128:131], v[192:195], v[4:7]
	v_mfma_f32_16x16x32_bf16 v[8:11], v[104:107], v[192:195], v[8:11]
	v_mfma_f32_16x16x32_bf16 v[8:11], v[92:95], v[188:191], v[8:11]
	s_barrier
	s_add_u32 s12, s12, 0x100
	s_addc_u32 s13, s13, 0
	s_add_u32 s20, s20, 0x100
	s_addc_u32 s21, s21, 0
	s_cmp_ge_i32 s45, s9
	s_mov_b32 s22, s45
	s_cbranch_scc0 .LBB0_1087
	s_and_b64 vcc, exec, s[42:43]
	s_cbranch_vccz .LBB0_1090
	s_barrier

; #define PG8_STAGE(bufoff, gbase, voff) do { _Pragma("unroll") for (int _i = 0; _i < 2; ++_i) \
;         __builtin_amdgcn_global_load_lds((const unsigned*)((const char*)(gbase) + (voff)[_i]), (PG8_LAS unsigned*)(lds + (bufoff) + ldsw + _i * 8192), 16, 0, 0); } while (0)
; #define PG8_LDA(dst, b, h) do { _Pragma("unroll") for (int m = 0; m < 4; ++m) _Pragma("unroll") for (int k = 0; k < 2; ++k) dst[m][k] = *(const PG8_LAS bf16x8*)(lds + PG8_SA(b, h) + aoff + m * 2048 + k * 1024); } while (0)
; #define PG8_LDB(dst, b, h) do { _Pragma("unroll") for (int n = 0; n < 2; ++n) _Pragma("unroll") for (int k = 0; k < 2; ++k) dst[n][k] = *(const PG8_LAS bf16x8*)(lds + PG8_SB(b, h) + boff + n * 2048 + k * 1024); } while (0)
; #define PG8_MMA(ai, bj, At, Bt) do { __builtin_amdgcn_s_setprio(1); _Pragma("unroll") for (int m = 0; m < 4; ++m) _Pragma("unroll") for (int n = 0; n < 2; ++n) _Pragma("unroll") for (int k = 0; k < 2; ++k) \
;         acc[ai][bj][m][n] = __builtin_amdgcn_mfma_f32_16x16x32_bf16(Bt[n][k], At[m][k], acc[ai][bj][m][n], 0, 0, 0); __builtin_amdgcn_s_setprio(0); } while (0)
; #define PG8_WAIT_V(n) asm volatile("s_waitcnt vmcnt(" #n ")" ::: "memory")
; #define PG8_WAIT_L(n) asm volatile("s_waitcnt lgkmcnt(" #n ")" ::: "memory")
; template <class Epi, class Sched, bool ALIGN_EPI = true>
; __device__ __forceinline__ void gemm_phase(PG8_LAS unsigned char* lds, const Gemm g, const Sched& S, const Epi& E, const int tid) {
;     ...
;         for (int t = 0; t < nt; t += 2) {
;             const bool last = (t == nt - 2);
;             const char* a1 = cA + (size_t)(t + 1) * kstep;
;             const char* a2 = last ? nA : cA + (size_t)(t + 2) * kstep; const char* b2 = last ? nB : cB + (size_t)(t + 2) * kstep;
;             const char* a3 = a2 + kstep; const char* b3 = b2 + kstep;
;             if (last && has_next) S.a_ready(nxt);
;             PG8_LDB(B0, 0, 0); PG8_LDB(B1, 0, 1); PG8_SCHED; PG8_LDA(At, 0, 0); PG8_STAGE(PG8_SA(1, 1), a1 + hstepA, voffA);
;             PG8_WAIT_V(8); PG8_WAIT_L(0); PG8_BAR; PG8_MMA(0, 0, At, B0); PG8_MMA(0, 1, At, B1); PG8_BAR; PG8_SCHED;
;             PG8_LDA(At, 0, 1); PG8_STAGE(PG8_SB(0, 0), b2, voffB); PG8_STAGE(PG8_SB(0, 1), b2 + hstepB, voffB); PG8_STAGE(PG8_SA(0, 0), a2, voffA);
;             PG8_WAIT_V(8); PG8_WAIT_L(0); PG8_BAR; PG8_MMA(1, 0, At, B0); PG8_MMA(1, 1, At, B1); PG8_BAR; PG8_SCHED;
.LBB0_1414:
	s_add_i32 s70, s12, 2
	s_add_u32 s10, s0, 0x100
	s_addc_u32 s11, s1, 0
	s_add_i32 s15, 0, 0x10000
	s_cmp_eq_u32 s45, s12
	s_cselect_b32 s23, s47, s11
	s_cselect_b32 s22, s46, s10
	s_cselect_b32 s13, s49, s69
	s_cselect_b32 s12, s48, s68
	s_add_i32 s16, 0, 0x14000
	v_add_u32_e32 v72, s15, v251
	v_add_u32_e32 v128, s16, v251
	ds_read_b128 v[56:59], v72
	ds_read_b128 v[60:63], v72 offset:1024
	ds_read_b128 v[68:71], v72 offset:2048
	ds_read_b128 v[72:75], v72 offset:3072
	ds_read_b128 v[92:95], v128
	ds_read_b128 v[104:107], v128 offset:1024
	ds_read_b128 v[116:119], v128 offset:2048
	ds_read_b128 v[128:131], v128 offset:3072
	s_add_i32 m0, s52, 0xc000
	ds_read_b128 v[140:143], v252
	ds_read_b128 v[152:155], v252 offset:1024
	ds_read_b128 v[156:159], v252 offset:2048
	ds_read_b128 v[160:163], v252 offset:3072
	ds_read_b128 v[172:175], v252 offset:4096
	ds_read_b128 v[184:187], v252 offset:5120
	ds_read_b128 v[188:191], v252 offset:6144
	ds_read_b128 v[192:195], v252 offset:7168
	global_load_lds_dwordx4 v216, s[0:1]
	s_add_i32 m0, s52, 0xe000
	s_nop 0
	global_load_lds_dwordx4 v218, s[0:1]
	s_waitcnt vmcnt(8)
	s_waitcnt lgkmcnt(0)
	s_barrier
	s_waitcnt lgkmcnt(0)
	v_mfma_f32_16x16x32_bf16 v[180:183], v[56:59], v[140:143], v[180:183]
	v_mfma_f32_16x16x32_bf16 v[180:183], v[60:63], v[152:155], v[180:183]
	v_mfma_f32_16x16x32_bf16 v[176:179], v[72:75], v[152:155], v[176:179]
	v_mfma_f32_16x16x32_bf16 v[176:179], v[68:71], v[140:143], v[176:179]
	v_mfma_f32_16x16x32_bf16 v[144:147], v[68:71], v[156:159], v[144:147]
	v_mfma_f32_16x16x32_bf16 v[144:147], v[72:75], v[160:163], v[144:147]
	v_mfma_f32_16x16x32_bf16 v[148:151], v[60:63], v[160:163], v[148:151]
	v_mfma_f32_16x16x32_bf16 v[148:151], v[56:59], v[156:159], v[148:151]
	v_mfma_f32_16x16x32_bf16 v[124:127], v[56:59], v[172:175], v[124:127]
	v_mfma_f32_16x16x32_bf16 v[124:127], v[60:63], v[184:187], v[124:127]
	v_mfma_f32_16x16x32_bf16 v[120:123], v[72:75], v[184:187], v[120:123]
	v_mfma_f32_16x16x32_bf16 v[120:123], v[68:71], v[172:175], v[120:123]
	v_mfma_f32_16x16x32_bf16 v[96:99], v[68:71], v[188:191], v[96:99]
	v_mfma_f32_16x16x32_bf16 v[96:99], v[72:75], v[192:195], v[96:99]
	v_mfma_f32_16x16x32_bf16 v[100:103], v[60:63], v[192:195], v[100:103]
	v_mfma_f32_16x16x32_bf16 v[100:103], v[56:59], v[188:191], v[100:103]
	v_mfma_f32_16x16x32_bf16 v[168:171], v[92:95], v[140:143], v[168:171]
	v_mfma_f32_16x16x32_bf16 v[168:171], v[104:107], v[152:155], v[168:171]
	v_mfma_f32_16x16x32_bf16 v[136:139], v[104:107], v[160:163], v[136:139]
	v_mfma_f32_16x16x32_bf16 v[136:139], v[92:95], v[156:159], v[136:139]
	v_mfma_f32_16x16x32_bf16 v[132:135], v[116:119], v[156:159], v[132:135]
	v_mfma_f32_16x16x32_bf16 v[132:135], v[128:131], v[160:163], v[132:135]
	v_mfma_f32_16x16x32_bf16 v[108:111], v[128:131], v[184:187], v[108:111]
	v_mfma_f32_16x16x32_bf16 v[108:111], v[116:119], v[172:175], v[108:111]
	v_mfma_f32_16x16x32_bf16 v[112:115], v[92:95], v[172:175], v[112:115]
	v_mfma_f32_16x16x32_bf16 v[112:115], v[104:107], v[184:187], v[112:115]
	v_mfma_f32_16x16x32_bf16 v[88:91], v[104:107], v[192:195], v[88:91]
	v_mfma_f32_16x16x32_bf16 v[88:91], v[92:95], v[188:191], v[88:91]
	v_mfma_f32_16x16x32_bf16 v[84:87], v[116:119], v[188:191], v[84:87]
	v_mfma_f32_16x16x32_bf16 v[84:87], v[128:131], v[192:195], v[84:87]
	v_mfma_f32_16x16x32_bf16 v[140:143], v[116:119], v[140:143], v[164:167]
	v_mfma_f32_16x16x32_bf16 v[140:143], v[128:131], v[152:155], v[140:143]
	s_barrier
	s_add_i32 s0, s15, s51
	s_mov_b32 m0, s0
	ds_read_b128 v[152:155], v252 offset:16384
	ds_read_b128 v[156:159], v252 offset:17408
	ds_read_b128 v[160:163], v252 offset:18432
	ds_read_b128 v[164:167], v252 offset:19456
	ds_read_b128 v[172:175], v252 offset:20480
	ds_read_b128 v[184:187], v252 offset:21504
	ds_read_b128 v[188:191], v252 offset:22528
	ds_read_b128 v[192:195], v252 offset:23552
	global_load_lds_dwordx4 v2, s[12:13]
	s_add_i32 m0, s0, 0x2000
	s_add_u32 s0, s12, 0x168000
	s_addc_u32 s1, s13, 0
	s_add_i32 s15, s16, s51
	global_load_lds_dwordx4 v214, s[12:13]
	s_mov_b32 m0, s15
	s_nop 0
	global_load_lds_dwordx4 v2, s[0:1]
	s_add_i32 m0, s15, 0x2000
	s_nop 0
	global_load_lds_dwordx4 v214, s[0:1]
	s_mov_b32 m0, s52
	s_nop 0
	global_load_lds_dwordx4 v210, s[22:23]
	s_mov_b32 m0, s53
	s_nop 0
	global_load_lds_dwordx4 v212, s[22:23]
	s_waitcnt vmcnt(8)
	s_waitcnt lgkmcnt(0)
	s_barrier
	s_waitcnt lgkmcnt(0)
	v_mfma_f32_16x16x32_bf16 v[80:83], v[56:59], v[152:155], v[80:83]
	v_mfma_f32_16x16x32_bf16 v[80:83], v[60:63], v[156:159], v[80:83]
	v_mfma_f32_16x16x32_bf16 v[76:79], v[72:75], v[156:159], v[76:79]
	v_mfma_f32_16x16x32_bf16 v[76:79], v[68:71], v[152:155], v[76:79]
	v_mfma_f32_16x16x32_bf16 v[44:47], v[68:71], v[160:163], v[44:47]
	v_mfma_f32_16x16x32_bf16 v[44:47], v[72:75], v[164:167], v[44:47]
	v_mfma_f32_16x16x32_bf16 v[48:51], v[60:63], v[164:167], v[48:51]
	v_mfma_f32_16x16x32_bf16 v[48:51], v[56:59], v[160:163], v[48:51]
	v_mfma_f32_16x16x32_bf16 v[32:35], v[56:59], v[172:175], v[32:35]
	v_mfma_f32_16x16x32_bf16 v[32:35], v[60:63], v[184:187], v[32:35]
	v_mfma_f32_16x16x32_bf16 v[28:31], v[72:75], v[184:187], v[28:31]
	v_mfma_f32_16x16x32_bf16 v[28:31], v[68:71], v[172:175], v[28:31]
	v_mfma_f32_16x16x32_bf16 v[12:15], v[68:71], v[188:191], v[12:15]
	v_mfma_f32_16x16x32_bf16 v[12:15], v[72:75], v[192:195], v[12:15]
	v_mfma_f32_16x16x32_bf16 v[16:19], v[60:63], v[192:195], v[16:19]
	v_mfma_f32_16x16x32_bf16 v[16:19], v[56:59], v[188:191], v[16:19]
	v_mfma_f32_16x16x32_bf16 v[52:55], v[116:119], v[152:155], v[52:55]
	v_mfma_f32_16x16x32_bf16 v[52:55], v[128:131], v[156:159], v[52:55]
	v_mfma_f32_16x16x32_bf16 v[36:39], v[128:131], v[164:167], v[36:39]
	v_mfma_f32_16x16x32_bf16 v[36:39], v[116:119], v[160:163], v[36:39]
	v_mfma_f32_16x16x32_bf16 v[40:43], v[92:95], v[160:163], v[40:43]
	v_mfma_f32_16x16x32_bf16 v[40:43], v[104:107], v[164:167], v[40:43]
	v_mfma_f32_16x16x32_bf16 v[24:27], v[104:107], v[184:187], v[24:27]
	v_mfma_f32_16x16x32_bf16 v[24:27], v[92:95], v[172:175], v[24:27]
	v_mfma_f32_16x16x32_bf16 v[20:23], v[116:119], v[172:175], v[20:23]
	v_mfma_f32_16x16x32_bf16 v[20:23], v[128:131], v[184:187], v[20:23]
	v_mfma_f32_16x16x32_bf16 v[4:7], v[128:131], v[192:195], v[4:7]
	v_mfma_f32_16x16x32_bf16 v[4:7], v[116:119], v[188:191], v[4:7]
	v_mfma_f32_16x16x32_bf16 v[8:11], v[92:95], v[188:191], v[8:11]
	v_mfma_f32_16x16x32_bf16 v[8:11], v[104:107], v[192:195], v[8:11]
	v_mfma_f32_16x16x32_bf16 v[56:59], v[92:95], v[152:155], v[64:67]
	v_mfma_f32_16x16x32_bf16 v[56:59], v[104:107], v[156:159], v[56:59]
	s_barrier
; #define PG8_STAGE(bufoff, gbase, voff) do { _Pragma("unroll") for (int _i = 0; _i < 2; ++_i) \
;         __builtin_amdgcn_global_load_lds((const unsigned*)((const char*)(gbase) + (voff)[_i]), (PG8_LAS unsigned*)(lds + (bufoff) + ldsw + _i * 8192), 16, 0, 0); } while (0)
; #define PG8_LDA(dst, b, h) do { _Pragma("unroll") for (int m = 0; m < 4; ++m) _Pragma("unroll") for (int k = 0; k < 2; ++k) dst[m][k] = *(const PG8_LAS bf16x8*)(lds + PG8_SA(b, h) + aoff + m * 2048 + k * 1024); } while (0)
; #define PG8_LDB(dst, b, h) do { _Pragma("unroll") for (int n = 0; n < 2; ++n) _Pragma("unroll") for (int k = 0; k < 2; ++k) dst[n][k] = *(const PG8_LAS bf16x8*)(lds + PG8_SB(b, h) + boff + n * 2048 + k * 1024); } while (0)
; #define PG8_MMA(ai, bj, At, Bt) do { __builtin_amdgcn_s_setprio(1); _Pragma("unroll") for (int m = 0; m < 4; ++m) _Pragma("unroll") for (int n = 0; n < 2; ++n) _Pragma("unroll") for (int k = 0; k < 2; ++k) \
;         acc[ai][bj][m][n] = __builtin_amdgcn_mfma_f32_16x16x32_bf16(Bt[n][k], At[m][k], acc[ai][bj][m][n], 0, 0, 0); __builtin_amdgcn_s_setprio(0); } while (0)
; #define PG8_WAIT_V(n) asm volatile("s_waitcnt vmcnt(" #n ")" ::: "memory")
; #define PG8_WAIT_L(n) asm volatile("s_waitcnt lgkmcnt(" #n ")" ::: "memory")
; #define PG8_BAR __builtin_amdgcn_s_barrier()
; #define PG8_SCHED __builtin_amdgcn_sched_barrier(0)
; template <class Epi, class Sched, bool ALIGN_EPI = true>
; __device__ __forceinline__ void gemm_phase(PG8_LAS unsigned char* lds, const Gemm g, const Sched& S, const Epi& E, const int tid) {
;     ...
;             PG8_LDB(B0, 1, 0); PG8_LDB(B1, 1, 1); PG8_SCHED; PG8_LDA(At, 1, 0); PG8_STAGE(PG8_SA(0, 1), a2 + hstepA, voffA);
;             PG8_WAIT_V(8); PG8_WAIT_L(0); PG8_BAR; PG8_MMA(0, 0, At, B0); PG8_MMA(0, 1, At, B1); PG8_BAR; PG8_SCHED;
;             PG8_LDA(At, 1, 1); PG8_STAGE(PG8_SB(1, 0), b3, voffB); PG8_STAGE(PG8_SB(1, 1), b3 + hstepB, voffB); PG8_STAGE(PG8_SA(1, 0), a3, voffA);
;             PG8_WAIT_V(8); PG8_WAIT_L(0); PG8_BAR; PG8_MMA(1, 0, At, B0); PG8_MMA(1, 1, At, B1); PG8_BAR; PG8_SCHED;
;         }
;         if constexpr (ALIGN_EPI) { if (wr == 0) PG8_BAR; }
;         E(acc, cur, wr, wc, fr, fq); S.done(cur);
;         if (!has_next) break;
	s_add_i32 s15, 0, 0x18000
	s_add_i32 s16, 0, 0x1c000
	v_add_u32_e32 v72, s15, v251
	v_add_u32_e32 v128, s16, v251
	ds_read_b128 v[60:63], v72
	ds_read_b128 v[64:67], v72 offset:1024
	ds_read_b128 v[68:71], v72 offset:2048
	ds_read_b128 v[72:75], v72 offset:3072
	ds_read_b128 v[92:95], v128
	ds_read_b128 v[104:107], v128 offset:1024
	ds_read_b128 v[116:119], v128 offset:2048
	ds_read_b128 v[128:131], v128 offset:3072
	s_add_u32 s0, s22, 0x168000
	s_addc_u32 s1, s23, 0
	s_mov_b32 m0, s54
	ds_read_b128 v[152:155], v252 offset:32768
	ds_read_b128 v[156:159], v252 offset:33792
	ds_read_b128 v[160:163], v252 offset:34816
	ds_read_b128 v[172:175], v252 offset:35840
	ds_read_b128 v[184:187], v252 offset:36864
	ds_read_b128 v[188:191], v252 offset:37888
	ds_read_b128 v[192:195], v252 offset:38912
	ds_read_b128 v[196:199], v252 offset:39936
	global_load_lds_dwordx4 v210, s[0:1]
	s_mov_b32 m0, s55
	s_nop 0
	global_load_lds_dwordx4 v212, s[0:1]
	s_waitcnt vmcnt(8)
	s_waitcnt lgkmcnt(0)
	s_barrier
	s_waitcnt lgkmcnt(0)
	v_mfma_f32_16x16x32_bf16 v[164:167], v[60:63], v[152:155], v[180:183]
	v_mfma_f32_16x16x32_bf16 v[180:183], v[64:67], v[156:159], v[164:167]
	v_mfma_f32_16x16x32_bf16 v[148:151], v[64:67], v[172:175], v[148:151]
	v_mfma_f32_16x16x32_bf16 v[148:151], v[60:63], v[160:163], v[148:151]
	v_mfma_f32_16x16x32_bf16 v[144:147], v[68:71], v[160:163], v[144:147]
	v_mfma_f32_16x16x32_bf16 v[144:147], v[72:75], v[172:175], v[144:147]
	v_mfma_f32_16x16x32_bf16 v[120:123], v[72:75], v[188:191], v[120:123]
	v_mfma_f32_16x16x32_bf16 v[120:123], v[68:71], v[184:187], v[120:123]
	v_mfma_f32_16x16x32_bf16 v[164:167], v[68:71], v[152:155], v[176:179]
	v_mfma_f32_16x16x32_bf16 v[176:179], v[72:75], v[156:159], v[164:167]
	v_mfma_f32_16x16x32_bf16 v[96:99], v[72:75], v[196:199], v[96:99]
	v_mfma_f32_16x16x32_bf16 v[96:99], v[68:71], v[192:195], v[96:99]
	v_mfma_f32_16x16x32_bf16 v[100:103], v[60:63], v[192:195], v[100:103]
	v_mfma_f32_16x16x32_bf16 v[100:103], v[64:67], v[196:199], v[100:103]
	v_mfma_f32_16x16x32_bf16 v[124:127], v[64:67], v[188:191], v[124:127]
	v_mfma_f32_16x16x32_bf16 v[124:127], v[60:63], v[184:187], v[124:127]
	v_mfma_f32_16x16x32_bf16 v[164:167], v[92:95], v[152:155], v[168:171]
	v_mfma_f32_16x16x32_bf16 v[168:171], v[104:107], v[156:159], v[164:167]
	v_mfma_f32_16x16x32_bf16 v[136:139], v[104:107], v[172:175], v[136:139]
	v_mfma_f32_16x16x32_bf16 v[136:139], v[92:95], v[160:163], v[136:139]
	v_mfma_f32_16x16x32_bf16 v[132:135], v[116:119], v[160:163], v[132:135]
	v_mfma_f32_16x16x32_bf16 v[132:135], v[128:131], v[172:175], v[132:135]
	v_mfma_f32_16x16x32_bf16 v[108:111], v[128:131], v[188:191], v[108:111]
	v_mfma_f32_16x16x32_bf16 v[108:111], v[116:119], v[184:187], v[108:111]
	v_mfma_f32_16x16x32_bf16 v[140:143], v[116:119], v[152:155], v[140:143]
	v_mfma_f32_16x16x32_bf16 v[164:167], v[128:131], v[156:159], v[140:143]
	v_mfma_f32_16x16x32_bf16 v[84:87], v[128:131], v[196:199], v[84:87]
	v_mfma_f32_16x16x32_bf16 v[84:87], v[116:119], v[192:195], v[84:87]
	v_mfma_f32_16x16x32_bf16 v[88:91], v[92:95], v[192:195], v[88:91]
	v_mfma_f32_16x16x32_bf16 v[88:91], v[104:107], v[196:199], v[88:91]
	v_mfma_f32_16x16x32_bf16 v[112:115], v[104:107], v[188:191], v[112:115]
	v_mfma_f32_16x16x32_bf16 v[112:115], v[92:95], v[184:187], v[112:115]
	s_barrier
	s_add_i32 s0, s15, s51
	s_mov_b32 m0, s0
	ds_read_b128 v[140:143], v252 offset:49152
	ds_read_b128 v[152:155], v252 offset:50176
	ds_read_b128 v[156:159], v252 offset:51200
	ds_read_b128 v[160:163], v252 offset:52224
	ds_read_b128 v[172:175], v252 offset:53248
	ds_read_b128 v[184:187], v252 offset:54272
	ds_read_b128 v[188:191], v252 offset:55296
	ds_read_b128 v[192:195], v252 offset:56320
	s_add_u32 s98, s12, 0x80
	s_addc_u32 s99, s13, 0
	global_load_lds_dwordx4 v2, s[98:99]
	s_add_i32 m0, s0, 0x2000
	s_add_u32 s0, s12, 0x168080
	s_addc_u32 s1, s13, 0
	s_add_i32 s12, s16, s51
	global_load_lds_dwordx4 v214, s[98:99]
	s_mov_b32 m0, s12
	s_nop 0
	global_load_lds_dwordx4 v2, s[0:1]
	s_add_i32 m0, s12, 0x2000
	s_nop 0
	global_load_lds_dwordx4 v214, s[0:1]
	s_mov_b32 m0, s58
	s_nop 0
	s_add_u32 s98, s22, 0x80
	s_addc_u32 s99, s23, 0
	global_load_lds_dwordx4 v210, s[98:99]
	s_mov_b32 m0, s59
	s_nop 0
	global_load_lds_dwordx4 v212, s[98:99]
	s_waitcnt vmcnt(8)
	s_waitcnt lgkmcnt(0)
	s_barrier
	s_waitcnt lgkmcnt(0)
	v_mfma_f32_16x16x32_bf16 v[80:83], v[60:63], v[140:143], v[80:83]
	v_mfma_f32_16x16x32_bf16 v[80:83], v[64:67], v[152:155], v[80:83]
	v_mfma_f32_16x16x32_bf16 v[76:79], v[72:75], v[152:155], v[76:79]
	v_mfma_f32_16x16x32_bf16 v[76:79], v[68:71], v[140:143], v[76:79]
	v_mfma_f32_16x16x32_bf16 v[44:47], v[68:71], v[156:159], v[44:47]
	v_mfma_f32_16x16x32_bf16 v[44:47], v[72:75], v[160:163], v[44:47]
	v_mfma_f32_16x16x32_bf16 v[48:51], v[64:67], v[160:163], v[48:51]
	v_mfma_f32_16x16x32_bf16 v[48:51], v[60:63], v[156:159], v[48:51]
	v_mfma_f32_16x16x32_bf16 v[32:35], v[60:63], v[172:175], v[32:35]
	v_mfma_f32_16x16x32_bf16 v[32:35], v[64:67], v[184:187], v[32:35]
	v_mfma_f32_16x16x32_bf16 v[28:31], v[72:75], v[184:187], v[28:31]
	v_mfma_f32_16x16x32_bf16 v[28:31], v[68:71], v[172:175], v[28:31]
	v_mfma_f32_16x16x32_bf16 v[12:15], v[68:71], v[188:191], v[12:15]
	v_mfma_f32_16x16x32_bf16 v[12:15], v[72:75], v[192:195], v[12:15]
	v_mfma_f32_16x16x32_bf16 v[16:19], v[64:67], v[192:195], v[16:19]
	v_mfma_f32_16x16x32_bf16 v[16:19], v[60:63], v[188:191], v[16:19]
	v_mfma_f32_16x16x32_bf16 v[56:59], v[92:95], v[140:143], v[56:59]
	v_mfma_f32_16x16x32_bf16 v[64:67], v[104:107], v[152:155], v[56:59]
	v_mfma_f32_16x16x32_bf16 v[52:55], v[128:131], v[152:155], v[52:55]
	v_mfma_f32_16x16x32_bf16 v[52:55], v[116:119], v[140:143], v[52:55]
	v_mfma_f32_16x16x32_bf16 v[36:39], v[116:119], v[156:159], v[36:39]
	v_mfma_f32_16x16x32_bf16 v[36:39], v[128:131], v[160:163], v[36:39]
	v_mfma_f32_16x16x32_bf16 v[40:43], v[104:107], v[160:163], v[40:43]
	v_mfma_f32_16x16x32_bf16 v[40:43], v[92:95], v[156:159], v[40:43]
	v_mfma_f32_16x16x32_bf16 v[24:27], v[92:95], v[172:175], v[24:27]
	v_mfma_f32_16x16x32_bf16 v[24:27], v[104:107], v[184:187], v[24:27]
	v_mfma_f32_16x16x32_bf16 v[20:23], v[128:131], v[184:187], v[20:23]
	v_mfma_f32_16x16x32_bf16 v[20:23], v[116:119], v[172:175], v[20:23]
	v_mfma_f32_16x16x32_bf16 v[4:7], v[116:119], v[188:191], v[4:7]
	v_mfma_f32_16x16x32_bf16 v[4:7], v[128:131], v[192:195], v[4:7]
	v_mfma_f32_16x16x32_bf16 v[8:11], v[104:107], v[192:195], v[8:11]
	v_mfma_f32_16x16x32_bf16 v[8:11], v[92:95], v[188:191], v[8:11]
	s_barrier
	s_add_u32 s68, s68, 0x100
	s_addc_u32 s69, s69, 0
	s_cmp_ge_i32 s70, s67
	s_mov_b64 s[0:1], s[10:11]
	s_mov_b32 s12, s70
	s_cbranch_scc0 .LBB0_1414
	s_nop 0
	s_nop 0
	s_nop 0
	s_nop 0
	s_nop 0
	s_nop 0
	s_nop 0
	s_nop 0
	s_nop 0
	s_nop 0
	s_nop 0
	s_nop 0
	s_and_b64 vcc, exec, s[42:43]
	s_cbranch_vccz .LBB0_1417
	s_barrier
